# v1 + NA attention: relative-position-bias table reads prefetched unconditionally (15 serialized LDS round trips removed per key tile); bit-identical
# speedup vs baseline: 1.0056x; 1.0056x over previous
; template <int MODE> __device__ __forceinline__ void modify(f32x16& p0, f32x16& p1, const Mod& M, int j, float& boff) {
;     ...
;       const int base = (kr - M.rq + 7) * 31 + 15 - M.c + 4 * M.hi; const int d0 = 4 * M.hi - M.cs;
; #pragma unroll
;       for (int r = 0; r < 16; ++r) { const int cr = (r & 3) + 8 * (r >> 2);
;         const bool v0 = (unsigned)(cr + d0) < 16u, v1 = (unsigned)(cr + 32 + d0) < 16u;
;         const float b0 = M.tab[v0 ? base + cr : 0], b1 = M.tab[v1 ? base + cr + 32 : 0];
;         p0[r] = v0 ? p0[r] + b0 : NEG; p1[r] = v1 ? p1[r] + b1 : NEG; }
.LBB0_388:
	s_or_b64 exec, exec, s[8:9]
	s_nop 2
	v_add_u32_e32 v80, 33, v154
	v_add_u32_e32 v151, 33, v153
	v_cmp_gt_u32_e64 s[6:7], 16, v80
	v_lshl_add_u32 v156, v153, 2, s10
	ds_read_b32 v232, v156 offset:4
	ds_read_b32 v233, v156 offset:8
	ds_read_b32 v234, v156 offset:12
	ds_read_b32 v235, v156 offset:32
	ds_read_b32 v236, v156 offset:36
	ds_read_b32 v237, v156 offset:40
	ds_read_b32 v238, v156 offset:44
	ds_read_b32 v239, v156 offset:64
	ds_read_b32 v240, v156 offset:68
	ds_read_b32 v241, v156 offset:72
	ds_read_b32 v242, v156 offset:76
	ds_read_b32 v243, v156 offset:96
	ds_read_b32 v244, v156 offset:100
	ds_read_b32 v245, v156 offset:104
	ds_read_b32 v246, v156 offset:108
	s_nop 0
	v_cndmask_b32_e64 v80, 0, v151, s[6:7]
	v_lshl_add_u32 v80, v80, 2, 0
	v_add_u32_e32 v80, 0x18800, v80
	ds_read_b32 v80, v80
	v_add_u32_e32 v151, 1, v154
	v_cmp_gt_u32_e64 s[8:9], 16, v151
	s_waitcnt lgkmcnt(0)
	s_and_saveexec_b64 s[12:13], s[8:9]
	s_cbranch_execz .LBB0_390
	v_mov_b32_e32 v149, v232
	v_add_f32_e32 v149, v81, v149
.LBB0_390:
	s_or_b64 exec, exec, s[12:13]
	v_add_u32_e32 v81, 34, v154
	v_add_u32_e32 v151, 34, v153
	v_cmp_gt_u32_e64 s[8:9], 16, v81
	s_nop 1
	v_cndmask_b32_e64 v81, 0, v151, s[8:9]
	v_lshl_add_u32 v81, v81, 2, 0
	v_add_u32_e32 v81, 0x18800, v81
	ds_read_b32 v155, v81
	v_add_u32_e32 v81, 2, v154
	v_cmp_gt_u32_e64 s[12:13], 16, v81
	v_mov_b32_e32 v81, 0xff800000
	v_mov_b32_e32 v151, 0xff800000
	s_and_saveexec_b64 s[14:15], s[12:13]
	s_cbranch_execz .LBB0_392
	v_mov_b32_e32 v151, v233
	v_add_f32_e32 v151, v82, v151
.LBB0_392:
	s_or_b64 exec, exec, s[14:15]
	v_add_u32_e32 v82, 35, v154
	v_add_u32_e32 v157, 35, v153
	v_cmp_gt_u32_e64 s[12:13], 16, v82
	s_nop 1
	v_cndmask_b32_e64 v82, 0, v157, s[12:13]
	v_lshl_add_u32 v82, v82, 2, 0
	v_add_u32_e32 v82, 0x18800, v82
	ds_read_b32 v157, v82
	v_add_u32_e32 v82, 3, v154
	v_cmp_gt_u32_e64 s[14:15], 16, v82
	s_and_saveexec_b64 s[16:17], s[14:15]
	s_cbranch_execz .LBB0_394
	v_mov_b32_e32 v81, v234
	v_add_f32_e32 v81, v83, v81
.LBB0_394:
	s_or_b64 exec, exec, s[16:17]
	v_add_u32_e32 v82, 40, v154
	v_add_u32_e32 v83, 40, v153
	v_cmp_gt_u32_e64 s[14:15], 16, v82
	s_nop 1
	v_cndmask_b32_e64 v82, 0, v83, s[14:15]
	v_lshl_add_u32 v82, v82, 2, 0
	v_add_u32_e32 v82, 0x18800, v82
	ds_read_b32 v158, v82
	v_add_u32_e32 v82, 8, v154
	v_cmp_gt_u32_e64 s[16:17], 16, v82
	v_mov_b32_e32 v82, 0xff800000
	v_mov_b32_e32 v83, 0xff800000
	s_and_saveexec_b64 s[18:19], s[16:17]
	s_cbranch_execz .LBB0_396
	v_mov_b32_e32 v83, v235
	v_add_f32_e32 v83, v84, v83
.LBB0_396:
	s_or_b64 exec, exec, s[18:19]
	v_add_u32_e32 v84, 41, v154
	v_add_u32_e32 v159, 41, v153
	v_cmp_gt_u32_e64 s[16:17], 16, v84
	s_nop 1
	v_cndmask_b32_e64 v84, 0, v159, s[16:17]
	v_lshl_add_u32 v84, v84, 2, 0
	v_add_u32_e32 v84, 0x18800, v84
	ds_read_b32 v159, v84
	v_add_u32_e32 v84, 9, v154
	v_cmp_gt_u32_e64 s[18:19], 16, v84
	s_and_saveexec_b64 s[20:21], s[18:19]
	s_cbranch_execz .LBB0_398
	v_mov_b32_e32 v82, v236
	v_add_f32_e32 v82, v85, v82
.LBB0_398:
	s_or_b64 exec, exec, s[20:21]
	v_add_u32_e32 v84, 42, v154
	v_add_u32_e32 v85, 42, v153
	v_cmp_gt_u32_e64 s[18:19], 16, v84
	s_nop 1
	v_cndmask_b32_e64 v84, 0, v85, s[18:19]
	v_lshl_add_u32 v84, v84, 2, 0
	v_add_u32_e32 v84, 0x18800, v84
	ds_read_b32 v160, v84
	v_add_u32_e32 v84, 10, v154
	v_cmp_gt_u32_e64 s[20:21], 16, v84
	v_mov_b32_e32 v84, 0xff800000
	v_mov_b32_e32 v85, 0xff800000
	s_and_saveexec_b64 s[22:23], s[20:21]
	s_cbranch_execz .LBB0_400
	v_mov_b32_e32 v85, v237
	v_add_f32_e32 v85, v86, v85
.LBB0_400:
	s_or_b64 exec, exec, s[22:23]
	v_add_u32_e32 v86, 43, v154
	v_add_u32_e32 v161, 43, v153
	v_cmp_gt_u32_e64 s[20:21], 16, v86
	s_nop 1
	v_cndmask_b32_e64 v86, 0, v161, s[20:21]
	v_lshl_add_u32 v86, v86, 2, 0
	v_add_u32_e32 v86, 0x18800, v86
	ds_read_b32 v161, v86
	v_add_u32_e32 v86, 11, v154
	v_cmp_gt_u32_e64 s[22:23], 16, v86
	s_and_saveexec_b64 s[24:25], s[22:23]
	s_cbranch_execz .LBB0_402
	v_mov_b32_e32 v84, v238
	v_add_f32_e32 v84, v87, v84
; template <int MODE> __device__ __forceinline__ void modify(f32x16& p0, f32x16& p1, const Mod& M, int j, float& boff) {
;     ...
;       const int base = (kr - M.rq + 7) * 31 + 15 - M.c + 4 * M.hi; const int d0 = 4 * M.hi - M.cs;
; #pragma unroll
;       for (int r = 0; r < 16; ++r) { const int cr = (r & 3) + 8 * (r >> 2);
;         const bool v0 = (unsigned)(cr + d0) < 16u, v1 = (unsigned)(cr + 32 + d0) < 16u;
;         const float b0 = M.tab[v0 ? base + cr : 0], b1 = M.tab[v1 ? base + cr + 32 : 0];
;         p0[r] = v0 ? p0[r] + b0 : NEG; p1[r] = v1 ? p1[r] + b1 : NEG; }
.LBB0_402:
	s_or_b64 exec, exec, s[24:25]
	s_movk_i32 s22, 0xffd0
	v_add_u32_e32 v86, 48, v153
	v_cmp_eq_u32_e64 s[22:23], s22, v162
	s_movk_i32 s24, 0xffef
	v_cmp_lt_u32_e64 s[24:25], s24, v154
	v_cndmask_b32_e64 v86, 0, v86, s[22:23]
	v_lshl_add_u32 v86, v86, 2, 0
	v_add_u32_e32 v86, 0x18800, v86
	ds_read_b32 v162, v86
	v_mov_b32_e32 v86, 0xff800000
	v_mov_b32_e32 v87, 0xff800000
	s_and_saveexec_b64 s[26:27], s[24:25]
	s_cbranch_execz .LBB0_404
	v_mov_b32_e32 v87, v239
	v_add_f32_e32 v87, v88, v87
.LBB0_404:
	s_or_b64 exec, exec, s[26:27]
	v_add_u32_e32 v88, 49, v154
	v_add_u32_e32 v163, 49, v153
	v_cmp_gt_u32_e64 s[24:25], 16, v88
	s_nop 1
	v_cndmask_b32_e64 v88, 0, v163, s[24:25]
	v_lshl_add_u32 v88, v88, 2, 0
	v_add_u32_e32 v88, 0x18800, v88
	ds_read_b32 v163, v88
	v_add_u32_e32 v88, 17, v154
	v_cmp_gt_u32_e64 s[26:27], 16, v88
	s_and_saveexec_b64 s[28:29], s[26:27]
	s_cbranch_execz .LBB0_406
	v_mov_b32_e32 v86, v240
	v_add_f32_e32 v86, v89, v86
.LBB0_406:
	s_or_b64 exec, exec, s[28:29]
	v_add_u32_e32 v88, 50, v154
	v_add_u32_e32 v89, 50, v153
	v_cmp_gt_u32_e64 s[26:27], 16, v88
	s_nop 1
	v_cndmask_b32_e64 v88, 0, v89, s[26:27]
	v_lshl_add_u32 v88, v88, 2, 0
	v_add_u32_e32 v88, 0x18800, v88
	ds_read_b32 v164, v88
	v_add_u32_e32 v88, 18, v154
	v_cmp_gt_u32_e64 s[28:29], 16, v88
	v_mov_b32_e32 v88, 0xff800000
	v_mov_b32_e32 v89, 0xff800000
	s_and_saveexec_b64 s[30:31], s[28:29]
	s_cbranch_execz .LBB0_408
	v_mov_b32_e32 v89, v241
	v_add_f32_e32 v89, v90, v89
.LBB0_408:
	s_or_b64 exec, exec, s[30:31]
	v_add_u32_e32 v90, 51, v154
	v_add_u32_e32 v165, 51, v153
	v_cmp_gt_u32_e64 s[28:29], 16, v90
	s_nop 1
	v_cndmask_b32_e64 v90, 0, v165, s[28:29]
	v_lshl_add_u32 v90, v90, 2, 0
	v_add_u32_e32 v90, 0x18800, v90
	ds_read_b32 v165, v90
	v_add_u32_e32 v90, 19, v154
	v_cmp_gt_u32_e64 s[30:31], 16, v90
	s_and_saveexec_b64 s[34:35], s[30:31]
	s_cbranch_execz .LBB0_410
	v_mov_b32_e32 v88, v242
	v_add_f32_e32 v88, v91, v88
.LBB0_410:
	s_or_b64 exec, exec, s[34:35]
	v_add_u32_e32 v90, 56, v154
	v_add_u32_e32 v91, 56, v153
	v_cmp_gt_u32_e64 s[30:31], 16, v90
	s_nop 1
	v_cndmask_b32_e64 v90, 0, v91, s[30:31]
	v_lshl_add_u32 v90, v90, 2, 0
	v_add_u32_e32 v90, 0x18800, v90
	ds_read_b32 v166, v90
	v_add_u32_e32 v90, 24, v154
	v_cmp_gt_u32_e64 s[34:35], 16, v90
	v_mov_b32_e32 v90, 0xff800000
	v_mov_b32_e32 v91, 0xff800000
	s_and_saveexec_b64 s[36:37], s[34:35]
	s_cbranch_execz .LBB0_412
	v_mov_b32_e32 v91, v243
	v_add_f32_e32 v91, v92, v91
.LBB0_412:
	s_or_b64 exec, exec, s[36:37]
	v_add_u32_e32 v92, 57, v154
	v_add_u32_e32 v167, 57, v153
	v_cmp_gt_u32_e64 s[34:35], 16, v92
	s_nop 1
	v_cndmask_b32_e64 v92, 0, v167, s[34:35]
	v_lshl_add_u32 v92, v92, 2, 0
	v_add_u32_e32 v92, 0x18800, v92
	ds_read_b32 v167, v92
	v_add_u32_e32 v92, 25, v154
	v_cmp_gt_u32_e64 s[36:37], 16, v92
	s_and_saveexec_b64 s[38:39], s[36:37]
	s_cbranch_execz .LBB0_414
	v_mov_b32_e32 v90, v244
	v_add_f32_e32 v90, v93, v90
.LBB0_414:
	s_or_b64 exec, exec, s[38:39]
	v_add_u32_e32 v92, 58, v154
	v_add_u32_e32 v93, 58, v153
	v_cmp_gt_u32_e64 s[36:37], 16, v92
	s_nop 1
	v_cndmask_b32_e64 v92, 0, v93, s[36:37]
	v_lshl_add_u32 v92, v92, 2, 0
	v_add_u32_e32 v92, 0x18800, v92
	ds_read_b32 v168, v92
	v_add_u32_e32 v92, 26, v154
	v_cmp_gt_u32_e64 s[38:39], 16, v92
	v_mov_b32_e32 v92, 0xff800000
	v_mov_b32_e32 v93, 0xff800000
	s_and_saveexec_b64 s[40:41], s[38:39]
	s_cbranch_execz .LBB0_416
	v_mov_b32_e32 v93, v245
	v_add_f32_e32 v93, v94, v93
.LBB0_416:
	s_or_b64 exec, exec, s[40:41]
	v_add_u32_e32 v94, 27, v154
	v_cmp_gt_u32_e64 s[40:41], 16, v94
	v_add_u32_e32 v94, 59, v154
	v_cmp_gt_u32_e64 s[38:39], 16, v94
	v_add_u32_e32 v94, 59, v153
	s_nop 0
	v_cndmask_b32_e64 v94, 0, v94, s[38:39]
	v_lshl_add_u32 v94, v94, 2, 0
	v_add_u32_e32 v94, 0x18800, v94
	ds_read_b32 v153, v94
	s_and_saveexec_b64 s[86:87], s[40:41]
	s_cbranch_execz .LBB0_418
	v_mov_b32_e32 v92, v246
	v_add_f32_e32 v92, v95, v92

; template <int MODE> __device__ __forceinline__ void modify(f32x16& p0, f32x16& p1, const Mod& M, int j, float& boff) {
;     ...
;       const int base = (kr - M.rq + 7) * 31 + 15 - M.c + 4 * M.hi; const int d0 = 4 * M.hi - M.cs;
; #pragma unroll
;       for (int r = 0; r < 16; ++r) { const int cr = (r & 3) + 8 * (r >> 2);
;         const bool v0 = (unsigned)(cr + d0) < 16u, v1 = (unsigned)(cr + 32 + d0) < 16u;
;         const float b0 = M.tab[v0 ? base + cr : 0], b1 = M.tab[v1 ? base + cr + 32 : 0];
;         p0[r] = v0 ? p0[r] + b0 : NEG; p1[r] = v1 ? p1[r] + b1 : NEG; }
.LBB0_1044:
	s_or_b64 exec, exec, s[14:15]
	s_nop 0
	v_add_u32_e32 v80, 33, v154
	v_add_u32_e32 v151, 33, v153
	v_cmp_gt_u32_e64 s[12:13], 16, v80
	v_lshl_add_u32 v156, v153, 2, s4
	ds_read_b32 v232, v156 offset:4
	ds_read_b32 v233, v156 offset:8
	ds_read_b32 v234, v156 offset:12
	ds_read_b32 v235, v156 offset:32
	ds_read_b32 v236, v156 offset:36
	ds_read_b32 v237, v156 offset:40
	ds_read_b32 v238, v156 offset:44
	ds_read_b32 v239, v156 offset:64
	ds_read_b32 v240, v156 offset:68
	ds_read_b32 v241, v156 offset:72
	ds_read_b32 v242, v156 offset:76
	ds_read_b32 v243, v156 offset:96
	ds_read_b32 v244, v156 offset:100
	ds_read_b32 v245, v156 offset:104
	ds_read_b32 v246, v156 offset:108
	s_nop 0
	v_cndmask_b32_e64 v80, 0, v151, s[12:13]
	v_lshl_add_u32 v80, v80, 2, 0
	v_add_u32_e32 v80, 0x18800, v80
	ds_read_b32 v80, v80
	v_add_u32_e32 v151, 1, v154
	v_cmp_gt_u32_e64 s[14:15], 16, v151
	s_waitcnt lgkmcnt(0)
	s_and_saveexec_b64 s[16:17], s[14:15]
	s_cbranch_execz .LBB0_1046
	v_mov_b32_e32 v149, v232
	v_add_f32_e32 v149, v81, v149
.LBB0_1046:
	s_or_b64 exec, exec, s[16:17]
	v_add_u32_e32 v81, 34, v154
	v_add_u32_e32 v151, 34, v153
	v_cmp_gt_u32_e64 s[14:15], 16, v81
	s_nop 1
	v_cndmask_b32_e64 v81, 0, v151, s[14:15]
	v_lshl_add_u32 v81, v81, 2, 0
	v_add_u32_e32 v81, 0x18800, v81
	ds_read_b32 v155, v81
	v_add_u32_e32 v81, 2, v154
	v_cmp_gt_u32_e64 s[16:17], 16, v81
	v_mov_b32_e32 v81, 0xff800000
	v_mov_b32_e32 v151, 0xff800000
	s_and_saveexec_b64 s[18:19], s[16:17]
	s_cbranch_execz .LBB0_1048
	v_mov_b32_e32 v151, v233
	v_add_f32_e32 v151, v82, v151
.LBB0_1048:
	s_or_b64 exec, exec, s[18:19]
	v_add_u32_e32 v82, 35, v154
	v_add_u32_e32 v157, 35, v153
	v_cmp_gt_u32_e64 s[16:17], 16, v82
	s_nop 1
	v_cndmask_b32_e64 v82, 0, v157, s[16:17]
	v_lshl_add_u32 v82, v82, 2, 0
	v_add_u32_e32 v82, 0x18800, v82
	ds_read_b32 v157, v82
	v_add_u32_e32 v82, 3, v154
	v_cmp_gt_u32_e64 s[18:19], 16, v82
	s_and_saveexec_b64 s[20:21], s[18:19]
	s_cbranch_execz .LBB0_1050
	v_mov_b32_e32 v81, v234
	v_add_f32_e32 v81, v83, v81
.LBB0_1050:
	s_or_b64 exec, exec, s[20:21]
	v_add_u32_e32 v82, 40, v154
	v_add_u32_e32 v83, 40, v153
	v_cmp_gt_u32_e64 s[18:19], 16, v82
	s_nop 1
	v_cndmask_b32_e64 v82, 0, v83, s[18:19]
	v_lshl_add_u32 v82, v82, 2, 0
	v_add_u32_e32 v82, 0x18800, v82
	ds_read_b32 v158, v82
	v_add_u32_e32 v82, 8, v154
	v_cmp_gt_u32_e64 s[20:21], 16, v82
	v_mov_b32_e32 v82, 0xff800000
	v_mov_b32_e32 v83, 0xff800000
	s_and_saveexec_b64 s[22:23], s[20:21]
	s_cbranch_execz .LBB0_1052
	v_mov_b32_e32 v83, v235
	v_add_f32_e32 v83, v84, v83
.LBB0_1052:
	s_or_b64 exec, exec, s[22:23]
	v_add_u32_e32 v84, 41, v154
	v_add_u32_e32 v159, 41, v153
	v_cmp_gt_u32_e64 s[20:21], 16, v84
	s_nop 1
	v_cndmask_b32_e64 v84, 0, v159, s[20:21]
	v_lshl_add_u32 v84, v84, 2, 0
	v_add_u32_e32 v84, 0x18800, v84
	ds_read_b32 v159, v84
	v_add_u32_e32 v84, 9, v154
	v_cmp_gt_u32_e64 s[22:23], 16, v84
	s_and_saveexec_b64 s[24:25], s[22:23]
	s_cbranch_execz .LBB0_1054
	v_mov_b32_e32 v82, v236
	v_add_f32_e32 v82, v85, v82
.LBB0_1054:
	s_or_b64 exec, exec, s[24:25]
	v_add_u32_e32 v84, 42, v154
	v_add_u32_e32 v85, 42, v153
	v_cmp_gt_u32_e64 s[22:23], 16, v84
	s_nop 1
	v_cndmask_b32_e64 v84, 0, v85, s[22:23]
	v_lshl_add_u32 v84, v84, 2, 0
	v_add_u32_e32 v84, 0x18800, v84
	ds_read_b32 v160, v84
	v_add_u32_e32 v84, 10, v154
	v_cmp_gt_u32_e64 s[24:25], 16, v84
	v_mov_b32_e32 v84, 0xff800000
	v_mov_b32_e32 v85, 0xff800000
	s_and_saveexec_b64 s[26:27], s[24:25]
	s_cbranch_execz .LBB0_1056
	v_mov_b32_e32 v85, v237
	v_add_f32_e32 v85, v86, v85
.LBB0_1056:
	s_or_b64 exec, exec, s[26:27]
	v_add_u32_e32 v86, 43, v154
	v_add_u32_e32 v161, 43, v153
	v_cmp_gt_u32_e64 s[24:25], 16, v86
	s_nop 1
	v_cndmask_b32_e64 v86, 0, v161, s[24:25]
	v_lshl_add_u32 v86, v86, 2, 0
	v_add_u32_e32 v86, 0x18800, v86
	ds_read_b32 v161, v86
	v_add_u32_e32 v86, 11, v154
	v_cmp_gt_u32_e64 s[26:27], 16, v86
	s_and_saveexec_b64 s[28:29], s[26:27]
	s_cbranch_execz .LBB0_1058
	v_mov_b32_e32 v84, v238
	v_add_f32_e32 v84, v87, v84
; template <int MODE> __device__ __forceinline__ void modify(f32x16& p0, f32x16& p1, const Mod& M, int j, float& boff) {
;     ...
;       const int base = (kr - M.rq + 7) * 31 + 15 - M.c + 4 * M.hi; const int d0 = 4 * M.hi - M.cs;
; #pragma unroll
;       for (int r = 0; r < 16; ++r) { const int cr = (r & 3) + 8 * (r >> 2);
;         const bool v0 = (unsigned)(cr + d0) < 16u, v1 = (unsigned)(cr + 32 + d0) < 16u;
;         const float b0 = M.tab[v0 ? base + cr : 0], b1 = M.tab[v1 ? base + cr + 32 : 0];
;         p0[r] = v0 ? p0[r] + b0 : NEG; p1[r] = v1 ? p1[r] + b1 : NEG; }
.LBB0_1058:
	s_or_b64 exec, exec, s[28:29]
	s_movk_i32 s26, 0xffd0
	v_add_u32_e32 v86, 48, v153
	v_cmp_eq_u32_e64 s[26:27], s26, v162
	s_movk_i32 s28, 0xffef
	v_cmp_lt_u32_e64 s[28:29], s28, v154
	v_cndmask_b32_e64 v86, 0, v86, s[26:27]
	v_lshl_add_u32 v86, v86, 2, 0
	v_add_u32_e32 v86, 0x18800, v86
	ds_read_b32 v162, v86
	v_mov_b32_e32 v86, 0xff800000
	v_mov_b32_e32 v87, 0xff800000
	s_and_saveexec_b64 s[30:31], s[28:29]
	s_cbranch_execz .LBB0_1060
	v_mov_b32_e32 v87, v239
	v_add_f32_e32 v87, v88, v87
.LBB0_1060:
	s_or_b64 exec, exec, s[30:31]
	v_add_u32_e32 v88, 49, v154
	v_add_u32_e32 v163, 49, v153
	v_cmp_gt_u32_e64 s[28:29], 16, v88
	s_nop 1
	v_cndmask_b32_e64 v88, 0, v163, s[28:29]
	v_lshl_add_u32 v88, v88, 2, 0
	v_add_u32_e32 v88, 0x18800, v88
	ds_read_b32 v163, v88
	v_add_u32_e32 v88, 17, v154
	v_cmp_gt_u32_e64 s[30:31], 16, v88
	s_and_saveexec_b64 s[34:35], s[30:31]
	s_cbranch_execz .LBB0_1062
	v_mov_b32_e32 v86, v240
	v_add_f32_e32 v86, v89, v86
.LBB0_1062:
	s_or_b64 exec, exec, s[34:35]
	v_add_u32_e32 v88, 50, v154
	v_add_u32_e32 v89, 50, v153
	v_cmp_gt_u32_e64 s[30:31], 16, v88
	s_nop 1
	v_cndmask_b32_e64 v88, 0, v89, s[30:31]
	v_lshl_add_u32 v88, v88, 2, 0
	v_add_u32_e32 v88, 0x18800, v88
	ds_read_b32 v164, v88
	v_add_u32_e32 v88, 18, v154
	v_cmp_gt_u32_e64 s[34:35], 16, v88
	v_mov_b32_e32 v88, 0xff800000
	v_mov_b32_e32 v89, 0xff800000
	s_and_saveexec_b64 s[36:37], s[34:35]
	s_cbranch_execz .LBB0_1064
	v_mov_b32_e32 v89, v241
	v_add_f32_e32 v89, v90, v89
.LBB0_1064:
	s_or_b64 exec, exec, s[36:37]
	v_add_u32_e32 v90, 51, v154
	v_add_u32_e32 v165, 51, v153
	v_cmp_gt_u32_e64 s[34:35], 16, v90
	s_nop 1
	v_cndmask_b32_e64 v90, 0, v165, s[34:35]
	v_lshl_add_u32 v90, v90, 2, 0
	v_add_u32_e32 v90, 0x18800, v90
	ds_read_b32 v165, v90
	v_add_u32_e32 v90, 19, v154
	v_cmp_gt_u32_e64 s[36:37], 16, v90
	s_and_saveexec_b64 s[38:39], s[36:37]
	s_cbranch_execz .LBB0_1066
	v_mov_b32_e32 v88, v242
	v_add_f32_e32 v88, v91, v88
.LBB0_1066:
	s_or_b64 exec, exec, s[38:39]
	v_add_u32_e32 v90, 56, v154
	v_add_u32_e32 v91, 56, v153
	v_cmp_gt_u32_e64 s[36:37], 16, v90
	s_nop 1
	v_cndmask_b32_e64 v90, 0, v91, s[36:37]
	v_lshl_add_u32 v90, v90, 2, 0
	v_add_u32_e32 v90, 0x18800, v90
	ds_read_b32 v166, v90
	v_add_u32_e32 v90, 24, v154
	v_cmp_gt_u32_e64 s[38:39], 16, v90
	v_mov_b32_e32 v90, 0xff800000
	v_mov_b32_e32 v91, 0xff800000
	s_and_saveexec_b64 s[40:41], s[38:39]
	s_cbranch_execz .LBB0_1068
	v_mov_b32_e32 v91, v243
	v_add_f32_e32 v91, v92, v91
.LBB0_1068:
	s_or_b64 exec, exec, s[40:41]
	v_add_u32_e32 v92, 57, v154
	v_add_u32_e32 v167, 57, v153
	v_cmp_gt_u32_e64 s[38:39], 16, v92
	s_nop 1
	v_cndmask_b32_e64 v92, 0, v167, s[38:39]
	v_lshl_add_u32 v92, v92, 2, 0
	v_add_u32_e32 v92, 0x18800, v92
	ds_read_b32 v167, v92
	v_add_u32_e32 v92, 25, v154
	v_cmp_gt_u32_e64 s[40:41], 16, v92
	s_and_saveexec_b64 s[42:43], s[40:41]
	s_cbranch_execz .LBB0_1070
	v_mov_b32_e32 v90, v244
	v_add_f32_e32 v90, v93, v90
.LBB0_1070:
	s_or_b64 exec, exec, s[42:43]
	v_add_u32_e32 v92, 58, v154
	v_add_u32_e32 v93, 58, v153
	v_cmp_gt_u32_e64 s[40:41], 16, v92
	s_nop 1
	v_cndmask_b32_e64 v92, 0, v93, s[40:41]
	v_lshl_add_u32 v92, v92, 2, 0
	v_add_u32_e32 v92, 0x18800, v92
	ds_read_b32 v168, v92
	v_add_u32_e32 v92, 26, v154
	v_cmp_gt_u32_e64 s[42:43], 16, v92
	v_mov_b32_e32 v92, 0xff800000
	v_mov_b32_e32 v93, 0xff800000
	s_and_saveexec_b64 s[46:47], s[42:43]
	s_cbranch_execz .LBB0_1072
	v_mov_b32_e32 v93, v245
	v_add_f32_e32 v93, v94, v93
.LBB0_1072:
	s_or_b64 exec, exec, s[46:47]
	v_add_u32_e32 v94, 27, v154
	v_cmp_gt_u32_e64 s[46:47], 16, v94
	v_add_u32_e32 v94, 59, v154
	v_cmp_gt_u32_e64 s[42:43], 16, v94
	v_add_u32_e32 v94, 59, v153
	s_nop 0
	v_cndmask_b32_e64 v94, 0, v94, s[42:43]
	v_lshl_add_u32 v94, v94, 2, 0
	v_add_u32_e32 v94, 0x18800, v94
	ds_read_b32 v153, v94
	s_and_saveexec_b64 s[84:85], s[46:47]
	s_cbranch_execz .LBB0_1074
	v_mov_b32_e32 v92, v246
	v_add_f32_e32 v92, v95, v92

; template <int MODE> __device__ __forceinline__ void modify(f32x16& p0, f32x16& p1, const Mod& M, int j, float& boff) {
;     ...
;       const int base = (kr - M.rq + 7) * 31 + 15 - M.c + 4 * M.hi; const int d0 = 4 * M.hi - M.cs;
; #pragma unroll
;       for (int r = 0; r < 16; ++r) { const int cr = (r & 3) + 8 * (r >> 2);
;         const bool v0 = (unsigned)(cr + d0) < 16u, v1 = (unsigned)(cr + 32 + d0) < 16u;
;         const float b0 = M.tab[v0 ? base + cr : 0], b1 = M.tab[v1 ? base + cr + 32 : 0];
;         p0[r] = v0 ? p0[r] + b0 : NEG; p1[r] = v1 ? p1[r] + b1 : NEG; }
.LBB0_1700:
	s_or_b64 exec, exec, s[8:9]
	s_nop 0
	v_add_u32_e32 v80, 33, v155
	v_add_u32_e32 v151, 33, v154
	v_cmp_gt_u32_e64 s[6:7], 16, v80
	v_lshl_add_u32 v157, v154, 2, s10
	ds_read_b32 v232, v157 offset:4
	ds_read_b32 v233, v157 offset:8
	ds_read_b32 v234, v157 offset:12
	ds_read_b32 v235, v157 offset:32
	ds_read_b32 v236, v157 offset:36
	ds_read_b32 v237, v157 offset:40
	ds_read_b32 v238, v157 offset:44
	ds_read_b32 v239, v157 offset:64
	ds_read_b32 v240, v157 offset:68
	ds_read_b32 v241, v157 offset:72
	ds_read_b32 v242, v157 offset:76
	ds_read_b32 v243, v157 offset:96
	ds_read_b32 v244, v157 offset:100
	ds_read_b32 v245, v157 offset:104
	ds_read_b32 v246, v157 offset:108
	s_nop 0
	v_cndmask_b32_e64 v80, 0, v151, s[6:7]
	v_lshl_add_u32 v80, v80, 2, 0
	v_add_u32_e32 v80, 0x18800, v80
	ds_read_b32 v153, v80
	v_add_u32_e32 v80, 1, v155
	v_cmp_gt_u32_e64 s[8:9], 16, v80
	s_waitcnt lgkmcnt(0)
	s_and_saveexec_b64 s[12:13], s[8:9]
	s_cbranch_execz .LBB0_1702
	v_mov_b32_e32 v80, v232
	v_add_f32_e32 v149, v81, v80
.LBB0_1702:
	s_or_b64 exec, exec, s[12:13]
	v_add_u32_e32 v80, 34, v155
	v_add_u32_e32 v81, 34, v154
	v_cmp_gt_u32_e64 s[8:9], 16, v80
	s_nop 1
	v_cndmask_b32_e64 v80, 0, v81, s[8:9]
	v_lshl_add_u32 v80, v80, 2, 0
	v_add_u32_e32 v80, 0x18800, v80
	ds_read_b32 v156, v80
	v_add_u32_e32 v80, 2, v155
	v_cmp_gt_u32_e64 s[12:13], 16, v80
	v_mov_b32_e32 v80, 0xff800000
	v_mov_b32_e32 v81, 0xff800000
	s_and_saveexec_b64 s[14:15], s[12:13]
	s_cbranch_execz .LBB0_1704
	v_mov_b32_e32 v81, v233
	v_add_f32_e32 v81, v82, v81
.LBB0_1704:
	s_or_b64 exec, exec, s[14:15]
	v_add_u32_e32 v82, 35, v155
	v_add_u32_e32 v151, 35, v154
	v_cmp_gt_u32_e64 s[12:13], 16, v82
	s_nop 1
	v_cndmask_b32_e64 v82, 0, v151, s[12:13]
	v_lshl_add_u32 v82, v82, 2, 0
	v_add_u32_e32 v82, 0x18800, v82
	ds_read_b32 v82, v82
	v_add_u32_e32 v151, 3, v155
	v_cmp_gt_u32_e64 s[14:15], 16, v151
	s_and_saveexec_b64 s[16:17], s[14:15]
	s_cbranch_execz .LBB0_1706
	v_mov_b32_e32 v80, v234
	v_add_f32_e32 v80, v83, v80
.LBB0_1706:
	s_or_b64 exec, exec, s[16:17]
	v_add_u32_e32 v83, 40, v155
	v_add_u32_e32 v151, 40, v154
	v_cmp_gt_u32_e64 s[14:15], 16, v83
	s_nop 1
	v_cndmask_b32_e64 v83, 0, v151, s[14:15]
	v_lshl_add_u32 v83, v83, 2, 0
	v_add_u32_e32 v83, 0x18800, v83
	ds_read_b32 v158, v83
	v_add_u32_e32 v83, 8, v155
	v_cmp_gt_u32_e64 s[16:17], 16, v83
	v_mov_b32_e32 v83, 0xff800000
	v_mov_b32_e32 v151, 0xff800000
	s_and_saveexec_b64 s[18:19], s[16:17]
	s_cbranch_execz .LBB0_1708
	v_mov_b32_e32 v151, v235
	v_add_f32_e32 v151, v84, v151
.LBB0_1708:
	s_or_b64 exec, exec, s[18:19]
	v_add_u32_e32 v84, 41, v155
	v_add_u32_e32 v159, 41, v154
	v_cmp_gt_u32_e64 s[16:17], 16, v84
	s_nop 1
	v_cndmask_b32_e64 v84, 0, v159, s[16:17]
	v_lshl_add_u32 v84, v84, 2, 0
	v_add_u32_e32 v84, 0x18800, v84
	ds_read_b32 v159, v84
	v_add_u32_e32 v84, 9, v155
	v_cmp_gt_u32_e64 s[18:19], 16, v84
	s_and_saveexec_b64 s[20:21], s[18:19]
	s_cbranch_execz .LBB0_1710
	v_mov_b32_e32 v83, v236
	v_add_f32_e32 v83, v85, v83
.LBB0_1710:
	s_or_b64 exec, exec, s[20:21]
	v_add_u32_e32 v84, 42, v155
	v_add_u32_e32 v85, 42, v154
	v_cmp_gt_u32_e64 s[18:19], 16, v84
	s_nop 1
	v_cndmask_b32_e64 v84, 0, v85, s[18:19]
	v_lshl_add_u32 v84, v84, 2, 0
	v_add_u32_e32 v84, 0x18800, v84
	ds_read_b32 v160, v84
	v_add_u32_e32 v84, 10, v155
	v_cmp_gt_u32_e64 s[20:21], 16, v84
	v_mov_b32_e32 v84, 0xff800000
	v_mov_b32_e32 v85, 0xff800000
	s_and_saveexec_b64 s[22:23], s[20:21]
	s_cbranch_execz .LBB0_1712
	v_mov_b32_e32 v85, v237
	v_add_f32_e32 v85, v86, v85
.LBB0_1712:
	s_or_b64 exec, exec, s[22:23]
	v_add_u32_e32 v86, 43, v155
	v_add_u32_e32 v161, 43, v154
	v_cmp_gt_u32_e64 s[20:21], 16, v86
	s_nop 1
	v_cndmask_b32_e64 v86, 0, v161, s[20:21]
	v_lshl_add_u32 v86, v86, 2, 0
	v_add_u32_e32 v86, 0x18800, v86
	ds_read_b32 v161, v86
	v_add_u32_e32 v86, 11, v155
	v_cmp_gt_u32_e64 s[22:23], 16, v86
	s_and_saveexec_b64 s[24:25], s[22:23]
	s_cbranch_execz .LBB0_1714
	v_mov_b32_e32 v84, v238
	v_add_f32_e32 v84, v87, v84
; template <int MODE> __device__ __forceinline__ void modify(f32x16& p0, f32x16& p1, const Mod& M, int j, float& boff) {
;     ...
;       const int base = (kr - M.rq + 7) * 31 + 15 - M.c + 4 * M.hi; const int d0 = 4 * M.hi - M.cs;
; #pragma unroll
;       for (int r = 0; r < 16; ++r) { const int cr = (r & 3) + 8 * (r >> 2);
;         const bool v0 = (unsigned)(cr + d0) < 16u, v1 = (unsigned)(cr + 32 + d0) < 16u;
;         const float b0 = M.tab[v0 ? base + cr : 0], b1 = M.tab[v1 ? base + cr + 32 : 0];
;         p0[r] = v0 ? p0[r] + b0 : NEG; p1[r] = v1 ? p1[r] + b1 : NEG; }
.LBB0_1714:
	s_or_b64 exec, exec, s[24:25]
	s_movk_i32 s22, 0xffd0
	v_add_u32_e32 v86, 48, v154
	v_cmp_eq_u32_e64 s[22:23], s22, v162
	s_movk_i32 s24, 0xffef
	v_cmp_lt_u32_e64 s[24:25], s24, v155
	v_cndmask_b32_e64 v86, 0, v86, s[22:23]
	v_lshl_add_u32 v86, v86, 2, 0
	v_add_u32_e32 v86, 0x18800, v86
	ds_read_b32 v162, v86
	v_mov_b32_e32 v86, 0xff800000
	v_mov_b32_e32 v87, 0xff800000
	s_and_saveexec_b64 s[26:27], s[24:25]
	s_cbranch_execz .LBB0_1716
	v_mov_b32_e32 v87, v239
	v_add_f32_e32 v87, v88, v87
.LBB0_1716:
	s_or_b64 exec, exec, s[26:27]
	v_add_u32_e32 v88, 49, v155
	v_add_u32_e32 v163, 49, v154
	v_cmp_gt_u32_e64 s[24:25], 16, v88
	s_nop 1
	v_cndmask_b32_e64 v88, 0, v163, s[24:25]
	v_lshl_add_u32 v88, v88, 2, 0
	v_add_u32_e32 v88, 0x18800, v88
	ds_read_b32 v163, v88
	v_add_u32_e32 v88, 17, v155
	v_cmp_gt_u32_e64 s[26:27], 16, v88
	s_and_saveexec_b64 s[28:29], s[26:27]
	s_cbranch_execz .LBB0_1718
	v_mov_b32_e32 v86, v240
	v_add_f32_e32 v86, v89, v86
.LBB0_1718:
	s_or_b64 exec, exec, s[28:29]
	v_add_u32_e32 v88, 50, v155
	v_add_u32_e32 v89, 50, v154
	v_cmp_gt_u32_e64 s[26:27], 16, v88
	s_nop 1
	v_cndmask_b32_e64 v88, 0, v89, s[26:27]
	v_lshl_add_u32 v88, v88, 2, 0
	v_add_u32_e32 v88, 0x18800, v88
	ds_read_b32 v164, v88
	v_add_u32_e32 v88, 18, v155
	v_cmp_gt_u32_e64 s[28:29], 16, v88
	v_mov_b32_e32 v88, 0xff800000
	v_mov_b32_e32 v89, 0xff800000
	s_and_saveexec_b64 s[30:31], s[28:29]
	s_cbranch_execz .LBB0_1720
	v_mov_b32_e32 v89, v241
	v_add_f32_e32 v89, v90, v89
.LBB0_1720:
	s_or_b64 exec, exec, s[30:31]
	v_add_u32_e32 v90, 51, v155
	v_add_u32_e32 v165, 51, v154
	v_cmp_gt_u32_e64 s[28:29], 16, v90
	s_nop 1
	v_cndmask_b32_e64 v90, 0, v165, s[28:29]
	v_lshl_add_u32 v90, v90, 2, 0
	v_add_u32_e32 v90, 0x18800, v90
	ds_read_b32 v165, v90
	v_add_u32_e32 v90, 19, v155
	v_cmp_gt_u32_e64 s[30:31], 16, v90
	s_and_saveexec_b64 s[34:35], s[30:31]
	s_cbranch_execz .LBB0_1722
	v_mov_b32_e32 v88, v242
	v_add_f32_e32 v88, v91, v88
.LBB0_1722:
	s_or_b64 exec, exec, s[34:35]
	v_add_u32_e32 v90, 56, v155
	v_add_u32_e32 v91, 56, v154
	v_cmp_gt_u32_e64 s[30:31], 16, v90
	s_nop 1
	v_cndmask_b32_e64 v90, 0, v91, s[30:31]
	v_lshl_add_u32 v90, v90, 2, 0
	v_add_u32_e32 v90, 0x18800, v90
	ds_read_b32 v166, v90
	v_add_u32_e32 v90, 24, v155
	v_cmp_gt_u32_e64 s[34:35], 16, v90
	v_mov_b32_e32 v90, 0xff800000
	v_mov_b32_e32 v91, 0xff800000
	s_and_saveexec_b64 s[36:37], s[34:35]
	s_cbranch_execz .LBB0_1724
	v_mov_b32_e32 v91, v243
	v_add_f32_e32 v91, v92, v91
.LBB0_1724:
	s_or_b64 exec, exec, s[36:37]
	v_add_u32_e32 v92, 57, v155
	v_add_u32_e32 v167, 57, v154
	v_cmp_gt_u32_e64 s[34:35], 16, v92
	s_nop 1
	v_cndmask_b32_e64 v92, 0, v167, s[34:35]
	v_lshl_add_u32 v92, v92, 2, 0
	v_add_u32_e32 v92, 0x18800, v92
	ds_read_b32 v167, v92
	v_add_u32_e32 v92, 25, v155
	v_cmp_gt_u32_e64 s[36:37], 16, v92
	s_and_saveexec_b64 s[38:39], s[36:37]
	s_cbranch_execz .LBB0_1726
	v_mov_b32_e32 v90, v244
	v_add_f32_e32 v90, v93, v90
.LBB0_1726:
	s_or_b64 exec, exec, s[38:39]
	v_add_u32_e32 v92, 58, v155
	v_add_u32_e32 v93, 58, v154
	v_cmp_gt_u32_e64 s[36:37], 16, v92
	s_nop 1
	v_cndmask_b32_e64 v92, 0, v93, s[36:37]
	v_lshl_add_u32 v92, v92, 2, 0
	v_add_u32_e32 v92, 0x18800, v92
	ds_read_b32 v168, v92
	v_add_u32_e32 v92, 26, v155
	v_cmp_gt_u32_e64 s[38:39], 16, v92
	v_mov_b32_e32 v92, 0xff800000
	v_mov_b32_e32 v93, 0xff800000
	s_and_saveexec_b64 s[40:41], s[38:39]
	s_cbranch_execz .LBB0_1728
	v_mov_b32_e32 v93, v245
	v_add_f32_e32 v93, v94, v93
.LBB0_1728:
	s_or_b64 exec, exec, s[40:41]
	v_add_u32_e32 v94, 27, v155
	v_cmp_gt_u32_e64 s[40:41], 16, v94
	v_add_u32_e32 v94, 59, v155
	v_cmp_gt_u32_e64 s[38:39], 16, v94
	v_add_u32_e32 v94, 59, v154
	s_nop 0
	v_cndmask_b32_e64 v94, 0, v94, s[38:39]
	v_lshl_add_u32 v94, v94, 2, 0
	v_add_u32_e32 v94, 0x18800, v94
	ds_read_b32 v154, v94
	s_and_saveexec_b64 s[64:65], s[40:41]
	s_cbranch_execz .LBB0_1730
	v_mov_b32_e32 v92, v246
	v_add_f32_e32 v92, v95, v92
